# v15 plus exact vmcnt counts on the loads-issued paths of the phase-A thin GEMM chunk loop (10 loads per step)
# speedup vs baseline: 1.0035x; 1.0027x over previous
.LBB0_412:
	s_cmp_lt_u32 s1, 6
	s_cselect_b64 s[8:9], -1, 0
	s_cmp_gt_u32 s1, 5
	s_cselect_b64 s[6:7], -1, 0
	s_and_b64 vcc, exec, s[6:7]
	s_cbranch_vccnz .Lta_s1skip
	v_lshl_add_u64 v[10:11], v[150:151], 0, s[4:5]
	v_add_co_u32_e32 v10, vcc, 0x1ca00000, v10
	v_lshl_add_u64 v[2:3], v[154:155], 0, s[4:5]
	v_lshl_add_u64 v[4:5], v[152:153], 0, s[4:5]
	v_addc_co_u32_e32 v11, vcc, 0, v11, vcc
	global_load_dwordx4 v[6:9], v[2:3], off offset:-512
	s_nop 0
	global_load_dwordx4 v[2:5], v[4:5], off offset:-512
	s_nop 0
	global_load_dwordx4 v[38:41], v[10:11], off offset:1024
	global_load_dwordx4 v[34:37], v[10:11], off offset:1088
	global_load_dwordx4 v[30:33], v[10:11], off offset:1152
	global_load_dwordx4 v[26:29], v[10:11], off offset:1216
	global_load_dwordx4 v[22:25], v[10:11], off offset:1280
	global_load_dwordx4 v[18:21], v[10:11], off offset:1344
	global_load_dwordx4 v[14:17], v[10:11], off offset:1408
	s_nop 0
	global_load_dwordx4 v[10:13], v[10:11], off offset:1472
	s_waitcnt vmcnt(20)
	s_branch .LBB0_414

.LBB0_414:
	s_bitcmp1_b32 s1, 0
	s_cselect_b32 s2, 0x4200, 0
	v_add_u32_e32 v160, s2, v159
	ds_read_b128 v[162:165], v160
	ds_read_b128 v[200:203], v160 offset:8448
	ds_read_b128 v[204:207], v160 offset:64
	ds_read_b128 v[208:211], v160 offset:8512
	ds_read_b128 v[214:217], v160 offset:128
	ds_read_b128 v[218:221], v160 offset:8576
	ds_read_b128 v[234:237], v160 offset:192
	ds_read_b128 v[238:241], v160 offset:8640
	ds_read_b128 v[242:245], v160 offset:256
	ds_read_b128 v[246:249], v160 offset:8704
	s_waitcnt lgkmcnt(9)
	v_mfma_f32_16x16x32_bf16 v[122:125], v[162:165], v[50:53], v[122:125]
	ds_read_b128 v[162:165], v160 offset:320
	s_waitcnt lgkmcnt(9)
	v_mfma_f32_16x16x32_bf16 v[126:129], v[200:203], v[50:53], v[126:129]
	ds_read_b128 v[200:203], v160 offset:8768
	s_waitcnt lgkmcnt(9)
	v_mfma_f32_16x16x32_bf16 v[122:125], v[204:207], v[54:57], v[122:125]
	ds_read_b128 v[204:207], v160 offset:384
	s_waitcnt lgkmcnt(9)
	v_mfma_f32_16x16x32_bf16 v[126:129], v[208:211], v[54:57], v[126:129]
	ds_read_b128 v[208:211], v160 offset:8832
	s_waitcnt lgkmcnt(9)
	v_mfma_f32_16x16x32_bf16 v[122:125], v[214:217], v[66:69], v[122:125]
	ds_read_b128 v[214:217], v160 offset:448
	s_waitcnt lgkmcnt(9)
	v_mfma_f32_16x16x32_bf16 v[126:129], v[218:221], v[66:69], v[126:129]
	ds_read_b128 v[218:221], v160 offset:8896
	s_waitcnt lgkmcnt(9)
	v_mfma_f32_16x16x32_bf16 v[122:125], v[234:237], v[70:73], v[122:125]
	s_waitcnt lgkmcnt(8)
	v_mfma_f32_16x16x32_bf16 v[126:129], v[238:241], v[70:73], v[126:129]
	s_waitcnt lgkmcnt(7)
	v_mfma_f32_16x16x32_bf16 v[122:125], v[242:245], v[74:77], v[122:125]
	s_waitcnt lgkmcnt(6)
	v_mfma_f32_16x16x32_bf16 v[126:129], v[246:249], v[74:77], v[126:129]
	s_waitcnt lgkmcnt(5)
	v_mfma_f32_16x16x32_bf16 v[122:125], v[162:165], v[78:81], v[122:125]
	s_waitcnt lgkmcnt(4)
	v_mfma_f32_16x16x32_bf16 v[126:129], v[200:203], v[78:81], v[126:129]
	s_waitcnt lgkmcnt(3)
	v_mfma_f32_16x16x32_bf16 v[122:125], v[204:207], v[86:89], v[122:125]
	s_waitcnt lgkmcnt(2)
	v_mfma_f32_16x16x32_bf16 v[126:129], v[208:211], v[86:89], v[126:129]
	s_waitcnt lgkmcnt(1)
	v_mfma_f32_16x16x32_bf16 v[122:125], v[214:217], v[94:97], v[122:125]
	s_waitcnt lgkmcnt(0)
	v_mfma_f32_16x16x32_bf16 v[126:129], v[218:221], v[94:97], v[126:129]
	s_cselect_b32 s3, 0, 0x4200
	s_add_i32 s11, s3, 0
	v_add_u32_e32 v162, s11, v157
	v_add_u32_e32 v161, s11, v158
	s_cmp_lg_u64 s[6:7], 0
	s_cbranch_scc1 .Lta_w1orig
	s_waitcnt vmcnt(18)
	ds_write_b128 v162, v[46:49]
	ds_write_b128 v161, v[62:65]
	s_branch .Lta_w1join
.Lta_w1orig:
	s_waitcnt vmcnt(9)
	ds_write_b128 v162, v[46:49]
	s_waitcnt vmcnt(8)
	ds_write_b128 v161, v[62:65]
.Lta_w1join:
	s_waitcnt lgkmcnt(0)
	s_barrier
	s_cmp_gt_u32 s1, 4
	s_cbranch_scc1 .LBB0_416
	v_lshl_add_u64 v[42:43], v[154:155], 0, s[4:5]
	v_lshl_add_u64 v[50:51], v[152:153], 0, s[4:5]
	global_load_dwordx4 v[42:45], v[42:43], off
	s_nop 0
	global_load_dwordx4 v[58:61], v[50:51], off
	v_lshl_add_u64 v[50:51], v[150:151], 0, s[4:5]
	v_add_co_u32_e32 v94, vcc, 0x1ca00000, v50
	s_nop 1
	v_addc_co_u32_e32 v95, vcc, 0, v51, vcc
	global_load_dwordx4 v[50:53], v[94:95], off offset:1536
	global_load_dwordx4 v[54:57], v[94:95], off offset:1600
	global_load_dwordx4 v[66:69], v[94:95], off offset:1664
	global_load_dwordx4 v[70:73], v[94:95], off offset:1728
	global_load_dwordx4 v[74:77], v[94:95], off offset:1792
	global_load_dwordx4 v[78:81], v[94:95], off offset:1856
	global_load_dwordx4 v[86:89], v[94:95], off offset:1920
	s_nop 0
	global_load_dwordx4 v[94:97], v[94:95], off offset:1984
.LBB0_416:
	s_cbranch_scc1 .Lta_s2slow
	s_waitcnt vmcnt(20)
	s_branch .Lta_s2go

.Lta_s2go:
	v_add_u32_e32 v161, s3, v159
	ds_read_b128 v[162:165], v161
	ds_read_b128 v[200:203], v161 offset:8448
	ds_read_b128 v[204:207], v161 offset:64
	ds_read_b128 v[208:211], v161 offset:8512
	ds_read_b128 v[214:217], v161 offset:128
	ds_read_b128 v[218:221], v161 offset:8576
	ds_read_b128 v[234:237], v161 offset:192
	ds_read_b128 v[238:241], v161 offset:8640
	ds_read_b128 v[242:245], v161 offset:256
	ds_read_b128 v[246:249], v161 offset:8704
	s_waitcnt lgkmcnt(9)
	v_mfma_f32_16x16x32_bf16 v[122:125], v[162:165], v[82:85], v[122:125]
	ds_read_b128 v[162:165], v161 offset:320
	s_waitcnt lgkmcnt(9)
	v_mfma_f32_16x16x32_bf16 v[126:129], v[200:203], v[82:85], v[126:129]
	ds_read_b128 v[200:203], v161 offset:8768
	s_waitcnt lgkmcnt(9)
	v_mfma_f32_16x16x32_bf16 v[122:125], v[204:207], v[90:93], v[122:125]
	ds_read_b128 v[204:207], v161 offset:384
	s_waitcnt lgkmcnt(9)
	v_mfma_f32_16x16x32_bf16 v[126:129], v[208:211], v[90:93], v[126:129]
	ds_read_b128 v[208:211], v161 offset:8832
	s_waitcnt lgkmcnt(9)
	v_mfma_f32_16x16x32_bf16 v[122:125], v[214:217], v[98:101], v[122:125]
	ds_read_b128 v[214:217], v161 offset:448
	s_waitcnt lgkmcnt(9)
	v_mfma_f32_16x16x32_bf16 v[126:129], v[218:221], v[98:101], v[126:129]
	ds_read_b128 v[218:221], v161 offset:8896
	s_waitcnt lgkmcnt(9)
	v_mfma_f32_16x16x32_bf16 v[122:125], v[234:237], v[102:105], v[122:125]
	s_waitcnt lgkmcnt(8)
	v_mfma_f32_16x16x32_bf16 v[126:129], v[238:241], v[102:105], v[126:129]
	s_waitcnt lgkmcnt(7)
	v_mfma_f32_16x16x32_bf16 v[122:125], v[242:245], v[106:109], v[122:125]
	s_waitcnt lgkmcnt(6)
	v_mfma_f32_16x16x32_bf16 v[126:129], v[246:249], v[106:109], v[126:129]
	s_waitcnt lgkmcnt(5)
	v_mfma_f32_16x16x32_bf16 v[122:125], v[162:165], v[110:113], v[122:125]
	s_waitcnt lgkmcnt(4)
	v_mfma_f32_16x16x32_bf16 v[126:129], v[200:203], v[110:113], v[126:129]
	s_waitcnt lgkmcnt(3)
	v_mfma_f32_16x16x32_bf16 v[122:125], v[204:207], v[114:117], v[122:125]
	s_waitcnt lgkmcnt(2)
	v_mfma_f32_16x16x32_bf16 v[126:129], v[208:211], v[114:117], v[126:129]
	s_waitcnt lgkmcnt(1)
	v_mfma_f32_16x16x32_bf16 v[122:125], v[214:217], v[118:121], v[122:125]
	s_waitcnt lgkmcnt(0)
	v_mfma_f32_16x16x32_bf16 v[126:129], v[218:221], v[118:121], v[126:129]
	s_andn2_b64 vcc, exec, s[8:9]
	s_cbranch_vccnz .LBB0_418
	s_add_i32 s2, s2, 0
	v_add_u32_e32 v162, s2, v157
	v_add_u32_e32 v161, s2, v158
	s_waitcnt vmcnt(18)
	ds_write_b128 v162, v[6:9]
	ds_write_b128 v161, v[2:5]

.LBB0_420:
	s_andn2_b64 vcc, exec, s[6:7]
	s_cbranch_vccnz .LBB0_425
	s_cmp_gt_u32 s1, 3
	s_cbranch_scc1 .Lta_s3skip
	v_lshl_add_u64 v[82:83], v[150:151], 0, s[4:5]
	v_add_co_u32_e32 v118, vcc, 0x1ca00000, v82
	v_lshl_add_u64 v[46:47], v[154:155], 0, s[4:5]
	v_lshl_add_u64 v[62:63], v[152:153], 0, s[4:5]
	v_addc_co_u32_e32 v119, vcc, 0, v83, vcc
	global_load_dwordx4 v[46:49], v[46:47], off offset:512
	s_nop 0
	global_load_dwordx4 v[62:65], v[62:63], off offset:512
	s_nop 0
	global_load_dwordx4 v[82:85], v[118:119], off offset:2048
	global_load_dwordx4 v[90:93], v[118:119], off offset:2112
	global_load_dwordx4 v[98:101], v[118:119], off offset:2176
	global_load_dwordx4 v[102:105], v[118:119], off offset:2240
	global_load_dwordx4 v[106:109], v[118:119], off offset:2304
	global_load_dwordx4 v[110:113], v[118:119], off offset:2368
	global_load_dwordx4 v[114:117], v[118:119], off offset:2432
	s_nop 0
	global_load_dwordx4 v[118:121], v[118:119], off offset:2496
	s_waitcnt vmcnt(20)
	s_mov_b32 s100, 1
	s_branch .LBB0_423
.Lta_s3skip:
	s_waitcnt vmcnt(10)
	s_mov_b32 s100, 0
.LBB0_423:
	ds_read_b128 v[162:165], v160
	ds_read_b128 v[200:203], v160 offset:8448
	ds_read_b128 v[204:207], v160 offset:64
	ds_read_b128 v[208:211], v160 offset:8512
	ds_read_b128 v[214:217], v160 offset:128
	ds_read_b128 v[218:221], v160 offset:8576
	ds_read_b128 v[234:237], v160 offset:192
	ds_read_b128 v[238:241], v160 offset:8640
	ds_read_b128 v[242:245], v160 offset:256
	ds_read_b128 v[246:249], v160 offset:8704
	s_waitcnt lgkmcnt(9)
	v_mfma_f32_16x16x32_bf16 v[122:125], v[162:165], v[38:41], v[122:125]
	ds_read_b128 v[162:165], v160 offset:320
	s_waitcnt lgkmcnt(9)
	v_mfma_f32_16x16x32_bf16 v[126:129], v[200:203], v[38:41], v[126:129]
	ds_read_b128 v[200:203], v160 offset:8768
	s_waitcnt lgkmcnt(9)
	v_mfma_f32_16x16x32_bf16 v[122:125], v[204:207], v[34:37], v[122:125]
	ds_read_b128 v[204:207], v160 offset:384
	s_waitcnt lgkmcnt(9)
	v_mfma_f32_16x16x32_bf16 v[126:129], v[208:211], v[34:37], v[126:129]
	ds_read_b128 v[208:211], v160 offset:8832
	s_waitcnt lgkmcnt(9)
	v_mfma_f32_16x16x32_bf16 v[122:125], v[214:217], v[30:33], v[122:125]
	ds_read_b128 v[214:217], v160 offset:448
	s_waitcnt lgkmcnt(9)
	v_mfma_f32_16x16x32_bf16 v[126:129], v[218:221], v[30:33], v[126:129]
	s_waitcnt lgkmcnt(8)
	v_mfma_f32_16x16x32_bf16 v[122:125], v[234:237], v[26:29], v[122:125]
	s_waitcnt lgkmcnt(7)
	v_mfma_f32_16x16x32_bf16 v[126:129], v[238:241], v[26:29], v[126:129]
	s_waitcnt lgkmcnt(6)
	v_mfma_f32_16x16x32_bf16 v[122:125], v[242:245], v[22:25], v[122:125]
	s_waitcnt lgkmcnt(5)
	v_mfma_f32_16x16x32_bf16 v[126:129], v[246:249], v[22:25], v[126:129]
	s_waitcnt lgkmcnt(4)
	v_mfma_f32_16x16x32_bf16 v[122:125], v[162:165], v[18:21], v[122:125]
	s_waitcnt lgkmcnt(3)
	v_mfma_f32_16x16x32_bf16 v[126:129], v[200:203], v[18:21], v[126:129]
	s_waitcnt lgkmcnt(2)
	v_mfma_f32_16x16x32_bf16 v[122:125], v[204:207], v[14:17], v[122:125]
	s_waitcnt lgkmcnt(1)
	v_mfma_f32_16x16x32_bf16 v[126:129], v[208:211], v[14:17], v[126:129]
	s_waitcnt lgkmcnt(0)
	v_mfma_f32_16x16x32_bf16 v[122:125], v[214:217], v[10:13], v[122:125]
	ds_read_b128 v[160:163], v160 offset:8896
	s_waitcnt lgkmcnt(0)
	v_mfma_f32_16x16x32_bf16 v[126:129], v[160:163], v[10:13], v[126:129]
	s_add_i32 s1, s1, 3
	s_cmpk_eq_i32 s4, 0xa00
	s_cbranch_scc1 .LBB0_411
	s_bitcmp1_b32 s1, 0
	s_cselect_b32 s2, 0x4200, 0
	s_add_i32 s2, s2, 0
	v_add_u32_e32 v161, s2, v157
	v_add_u32_e32 v160, s2, v158
	s_cmp_eq_u32 s100, 1
	s_cbranch_scc1 .Lta_w3f
	s_waitcnt vmcnt(8)
	s_branch .Lta_w3j
.Lta_w3f:
	s_waitcnt vmcnt(18)
.Lta_w3j:
	ds_write_b128 v161, v[42:45]
	ds_write_b128 v160, v[58:61]
	s_branch .LBB0_411

.LBB0_1971:
	s_andn2_b64 vcc, exec, s[8:9]
	s_cbranch_vccnz .LBB0_1976
	s_cmp_gt_u32 s2, 6
	s_cbranch_scc1 .Lti_s3skip
	v_lshl_add_u64 v[58:59], v[178:179], 0, s[4:5]
	v_lshl_add_u64 v[70:71], v[180:181], 0, s[4:5]
	v_lshl_add_u64 v[90:91], v[182:183], 0, s[4:5]
	v_lshl_add_u64 v[106:107], v[184:185], 0, s[4:5]
	v_lshl_add_u64 v[142:143], v[176:177], 0, s[4:5]
	global_load_dwordx4 v[58:61], v[58:59], off
	s_nop 0
	global_load_dwordx4 v[70:73], v[70:71], off
	s_nop 0
	global_load_dwordx4 v[90:93], v[90:91], off
	s_nop 0
	global_load_dwordx4 v[106:109], v[106:107], off
	s_nop 0
	global_load_dwordx4 v[114:117], v[142:143], off offset:256
	global_load_dwordx4 v[118:121], v[142:143], off offset:320
	global_load_dwordx4 v[122:125], v[142:143], off offset:384
	global_load_dwordx4 v[126:129], v[142:143], off offset:448
	global_load_dwordx4 v[130:133], v[142:143], off offset:512
	global_load_dwordx4 v[134:137], v[142:143], off offset:576
	global_load_dwordx4 v[138:141], v[142:143], off offset:640
	s_nop 0
	global_load_dwordx4 v[142:145], v[142:143], off offset:704
	s_waitcnt vmcnt(24)
	s_mov_b32 s100, 1
	s_branch .LBB0_1974
.Lti_s3skip:
	s_waitcnt vmcnt(12)
	s_mov_b32 s100, 0
.LBB0_1974:
	ds_read_b128 v[194:197], v213
	ds_read_b128 v[200:203], v213 offset:8448
	ds_read_b128 v[204:207], v213 offset:64
	ds_read_b128 v[214:217], v213 offset:8512
	ds_read_b128 v[218:221], v213 offset:128
	ds_read_b128 v[234:237], v213 offset:8576
	ds_read_b128 v[238:241], v213 offset:192
	ds_read_b128 v[242:245], v213 offset:8640
	ds_read_b128 v[246:249], v213 offset:256
	s_waitcnt lgkmcnt(8)
	v_mfma_f32_16x16x32_bf16 v[146:149], v[194:197], v[46:49], v[146:149]
	ds_read_b128 v[194:197], v213 offset:8704
	s_waitcnt lgkmcnt(8)
	v_mfma_f32_16x16x32_bf16 v[150:153], v[200:203], v[46:49], v[150:153]
	ds_read_b128 v[200:203], v213 offset:320
	s_waitcnt lgkmcnt(8)
	v_mfma_f32_16x16x32_bf16 v[146:149], v[204:207], v[42:45], v[146:149]
	ds_read_b128 v[204:207], v213 offset:8768
	s_waitcnt lgkmcnt(8)
	v_mfma_f32_16x16x32_bf16 v[150:153], v[214:217], v[42:45], v[150:153]
	ds_read_b128 v[214:217], v213 offset:384
	s_waitcnt lgkmcnt(8)
	v_mfma_f32_16x16x32_bf16 v[146:149], v[218:221], v[38:41], v[146:149]
	ds_read_b128 v[218:221], v213 offset:8832
	s_waitcnt lgkmcnt(8)
	v_mfma_f32_16x16x32_bf16 v[150:153], v[234:237], v[38:41], v[150:153]
	ds_read_b128 v[234:237], v213 offset:448
	s_waitcnt lgkmcnt(8)
	v_mfma_f32_16x16x32_bf16 v[146:149], v[238:241], v[34:37], v[146:149]
	ds_read_b128 v[238:241], v213 offset:8896
	s_waitcnt lgkmcnt(8)
	v_mfma_f32_16x16x32_bf16 v[150:153], v[242:245], v[34:37], v[150:153]
	s_waitcnt lgkmcnt(7)
	v_mfma_f32_16x16x32_bf16 v[146:149], v[246:249], v[30:33], v[146:149]
	s_waitcnt lgkmcnt(6)
	v_mfma_f32_16x16x32_bf16 v[150:153], v[194:197], v[30:33], v[150:153]
	s_waitcnt lgkmcnt(5)
	v_mfma_f32_16x16x32_bf16 v[146:149], v[200:203], v[26:29], v[146:149]
	s_waitcnt lgkmcnt(4)
	v_mfma_f32_16x16x32_bf16 v[150:153], v[204:207], v[26:29], v[150:153]
	s_waitcnt lgkmcnt(3)
	v_mfma_f32_16x16x32_bf16 v[146:149], v[214:217], v[22:25], v[146:149]
	s_waitcnt lgkmcnt(2)
	v_mfma_f32_16x16x32_bf16 v[150:153], v[218:221], v[22:25], v[150:153]
	s_waitcnt lgkmcnt(1)
	v_mfma_f32_16x16x32_bf16 v[146:149], v[234:237], v[18:21], v[146:149]
	s_waitcnt lgkmcnt(0)
	v_mfma_f32_16x16x32_bf16 v[150:153], v[238:241], v[18:21], v[150:153]
	s_add_i32 s2, s2, 3
	s_cmpk_eq_i32 s4, 0x1000
	s_cbranch_scc1 .LBB0_1962
	s_bitcmp1_b32 s2, 0
	s_cselect_b32 s3, 0x8400, 0
	s_add_i32 s3, s3, 0
	v_add_u32_e32 v197, s3, v187
	v_add_u32_e32 v194, s3, v190
	v_add_u32_e32 v195, s3, v189
	v_add_u32_e32 v196, s3, v188
	s_cmp_eq_u32 s100, 1
	s_cbranch_scc1 .Lti_w3f
	s_waitcnt vmcnt(8)
	s_branch .Lti_w3j
